# weight-conversion loops of the FFN-up L1 tail slot: all 8 loads in flight (spare bank v192-215: v234-240 hold values live across phases); rw_mix L0: four x_prev loads issued together
# speedup vs baseline: 1.0152x; 1.0023x over previous
.LBB0_139:
	s_mov_b32 s0, 0x8000
	v_readlane_b32 s72, v252, 58
	v_cmp_gt_i32_e32 vcc, s0, v146
	v_readlane_b32 s73, v252, 59
	v_mov_b32_e32 v130, s89
	s_and_b64 s[0:1], s[12:13], vcc
	v_mov_b32_e32 v131, s73
	v_ashrrev_i32_e32 v147, 31, v146
	v_cndmask_b32_e64 v159, v130, v131, s[0:1]
	v_mov_b32_e32 v130, s88
	v_mov_b32_e32 v131, s72
	v_cndmask_b32_e64 v158, v130, v131, s[0:1]
	v_lshlrev_b64 v[130:131], 12, v[146:147]
	v_lshl_add_u64 v[130:131], v[158:159], 0, v[130:131]
	v_lshlrev_b32_e32 v150, 2, v148
	v_lshl_add_u64 v[142:143], v[130:131], 0, v[150:151]
	global_load_dwordx4 v[130:133], v[142:143], off
	global_load_dwordx4 v[134:137], v[142:143], off offset:1024
	global_load_dwordx4 v[138:141], v[142:143], off offset:2048
	s_nop 0
	global_load_dwordx4 v[142:145], v[142:143], off offset:3072
	v_lshrrev_b32_e32 v149, 21, v147
	v_add_u32_e32 v149, v146, v149
	v_ashrrev_i32_e32 v160, 11, v149
	v_mul_i32_i24_e32 v149, 0x800, v160
	v_sub_u32_e32 v149, v146, v149
	v_cndmask_b32_e32 v149, v171, v149, vcc
	v_cmp_gt_i32_e64 s[6:7], 1, v149
	v_cmp_lt_i32_e64 s[0:1], 0, v149
	v_mov_b32_e32 v161, v151
	v_readlane_b32 s74, v252, 60
	v_readlane_b32 s75, v252, 61
	v_readlane_b32 s76, v252, 62
	v_readlane_b32 s77, v252, 63
	v_readlane_b32 s78, v251, 0
	v_readlane_b32 s79, v251, 1
	v_readlane_b32 s80, v251, 2
	v_readlane_b32 s81, v251, 3
	v_readlane_b32 s82, v251, 4
	v_readlane_b32 s83, v251, 5
	v_readlane_b32 s84, v251, 6
	v_readlane_b32 s85, v251, 7
	v_readlane_b32 s86, v251, 8
	v_readlane_b32 s87, v251, 9
	s_and_saveexec_b64 s[8:9], s[0:1]
	s_cbranch_execz .LBB0_141
	v_add_u32_e32 v114, -1, v146
	v_ashrrev_i32_e32 v115, 31, v114
	v_lshlrev_b64 v[114:115], 12, v[114:115]
	v_lshl_add_u64 v[114:115], v[158:159], 0, v[114:115]
	v_lshl_add_u64 v[126:127], v[114:115], 0, v[150:151]
	global_load_dwordx4 v[114:117], v[126:127], off
	global_load_dwordx4 v[118:121], v[126:127], off offset:1024
	global_load_dwordx4 v[122:125], v[126:127], off offset:2048
	s_nop 0
	global_load_dwordx4 v[126:129], v[126:127], off offset:3072
	s_waitcnt vmcnt(3)
	v_pk_mul_f32 v[190:191], v[116:117], v[116:117]
	v_pk_mul_f32 v[192:193], v[114:115], v[114:115]
	s_nop 0
	v_pk_mov_b32 v[194:195], v[192:193], v[190:191] op_sel:[1,0]
	v_mov_b32_e32 v193, v191
	v_pk_add_f32 v[158:159], v[194:195], v[192:193]
	v_pk_add_f32 v[158:159], v[158:159], v[158:159] op_sel:[0,1] op_sel_hi:[1,0]
	s_waitcnt vmcnt(2)
	v_pk_mul_f32 v[196:197], v[120:121], v[120:121]
	v_pk_mul_f32 v[198:199], v[118:119], v[118:119]
	s_nop 0
	v_pk_mov_b32 v[200:201], v[198:199], v[196:197] op_sel:[1,0]
	v_mov_b32_e32 v199, v197
	v_pk_add_f32 v[162:163], v[200:201], v[198:199]
	v_pk_add_f32 v[162:163], v[162:163], v[162:163] op_sel:[0,1] op_sel_hi:[1,0]
	s_waitcnt vmcnt(0)
	v_mul_f32_e32 v161, v126, v126
	v_mul_f32_e32 v164, v127, v127
	v_mov_b32_e32 v159, v161
	v_mov_b32_e32 v163, v164
	v_pk_add_f32 v[158:159], v[158:159], v[162:163]
	v_mul_f32_e32 v162, v123, v123
	v_mul_f32_e32 v164, v125, v125
	v_mul_f32_e32 v175, v128, v128
	v_mul_f32_e32 v178, v129, v129
	v_pk_fma_f32 v[162:163], v[122:123], v[122:123], v[162:163] op_sel_hi:[1,1,0]
	v_pk_fma_f32 v[176:177], v[124:125], v[124:125], v[164:165] op_sel_hi:[1,1,0]
	v_mov_b32_e32 v163, v175
	v_mov_b32_e32 v177, v178
	v_pk_add_f32 v[162:163], v[162:163], v[176:177]
	s_nop 0
	v_pk_add_f32 v[158:159], v[158:159], v[162:163]
	s_nop 0
	v_add_f32_e32 v161, v158, v159

.LBB0_1962:
	v_ashrrev_i32_e32 v6, 31, v40
	v_lshrrev_b32_e32 v6, 25, v6
	v_add_u32_e32 v6, v40, v6
	v_ashrrev_i32_e32 v6, 7, v6
	v_lshlrev_b32_e32 v8, 6, v6
	v_lshlrev_b32_e32 v6, 12, v6
	v_sub_u32_e32 v6, v24, v6
	v_or_b32_e32 v42, v8, v12
	v_ashrrev_i32_e32 v7, 31, v6
	v_ashrrev_i32_e32 v43, 31, v42
	v_lshl_add_u64 v[10:11], v[6:7], 2, v[2:3]
	v_lshlrev_b64 v[42:43], 14, v[42:43]
	v_or_b32_e32 v46, v8, v13
	v_lshl_add_u64 v[42:43], v[10:11], 0, v[42:43]
	v_ashrrev_i32_e32 v47, 31, v46
	global_load_dwordx4 v[42:45], v[42:43], off
	v_lshlrev_b64 v[46:47], 14, v[46:47]
	v_lshl_add_u64 v[46:47], v[10:11], 0, v[46:47]
	global_load_dwordx4 v[46:49], v[46:47], off
	v_add_u32_e32 v6, v6, v12
	v_ashrrev_i32_e32 v9, 31, v8
	v_ashrrev_i32_e32 v7, 31, v6
	v_add_u32_e32 v40, s4, v40
	s_movk_i32 s0, 0x7ff
	v_cmp_lt_i32_e64 s[0:1], s0, v40
	v_add_u32_e32 v24, s5, v24
	s_or_b64 s[6:7], s[0:1], s[6:7]
	v_or_b32_e32 v192, v8, v14
	v_ashrrev_i32_e32 v193, 31, v192
	v_lshlrev_b64 v[192:193], 14, v[192:193]
	v_or_b32_e32 v196, v8, v15
	v_lshl_add_u64 v[192:193], v[10:11], 0, v[192:193]
	v_ashrrev_i32_e32 v197, 31, v196
	global_load_dwordx4 v[192:195], v[192:193], off
	v_lshlrev_b64 v[196:197], 14, v[196:197]
	v_lshl_add_u64 v[196:197], v[10:11], 0, v[196:197]
	global_load_dwordx4 v[196:199], v[196:197], off
	v_or_b32_e32 v200, v8, v16
	v_ashrrev_i32_e32 v201, 31, v200
	v_lshlrev_b64 v[200:201], 14, v[200:201]
	v_or_b32_e32 v204, v8, v17
	v_lshl_add_u64 v[200:201], v[10:11], 0, v[200:201]
	v_ashrrev_i32_e32 v205, 31, v204
	global_load_dwordx4 v[200:203], v[200:201], off
	v_lshlrev_b64 v[204:205], 14, v[204:205]
	v_lshl_add_u64 v[204:205], v[10:11], 0, v[204:205]
	global_load_dwordx4 v[204:207], v[204:205], off
	v_or_b32_e32 v208, v8, v18
	v_ashrrev_i32_e32 v209, 31, v208
	v_lshlrev_b64 v[208:209], 14, v[208:209]
	v_or_b32_e32 v212, v8, v19
	v_lshl_add_u64 v[208:209], v[10:11], 0, v[208:209]
	v_ashrrev_i32_e32 v213, 31, v212
	global_load_dwordx4 v[208:211], v[208:209], off
	v_lshlrev_b64 v[212:213], 14, v[212:213]
	v_lshl_add_u64 v[10:11], v[10:11], 0, v[212:213]
	global_load_dwordx4 v[212:215], v[10:11], off
	v_lshl_add_u64 v[8:9], v[8:9], 1, v[4:5]
	s_waitcnt vmcnt(7)
	ds_write2_b32 v25, v42, v43 offset1:1
	ds_write2_b32 v25, v44, v45 offset0:2 offset1:3
	s_waitcnt vmcnt(6)
	ds_write2_b32 v26, v46, v47 offset1:1
	ds_write2_b32 v27, v48, v49 offset1:1
	s_waitcnt vmcnt(5)
	ds_write2_b32 v28, v192, v193 offset1:1
	ds_write2_b32 v29, v194, v195 offset1:1
	s_waitcnt vmcnt(4)
	ds_write2_b32 v30, v196, v197 offset1:1
	ds_write2_b32 v31, v198, v199 offset1:1
	s_waitcnt lgkmcnt(7)
	s_waitcnt vmcnt(3)
	ds_write2_b32 v32, v200, v201 offset1:1
	ds_write2_b32 v33, v202, v203 offset1:1
	s_waitcnt vmcnt(2)
	ds_write2_b32 v34, v204, v205 offset1:1
	ds_write2_b32 v35, v206, v207 offset1:1
	s_waitcnt vmcnt(1)
	ds_write2_b32 v36, v208, v209 offset1:1
	ds_write2_b32 v37, v210, v211 offset1:1
	s_waitcnt vmcnt(0)
	ds_write2_b32 v38, v212, v213 offset1:1
	ds_write2_b32 v39, v214, v215 offset1:1
	s_waitcnt lgkmcnt(0)
	ds_read2_b32 v[10:11], v23 offset1:33
	s_waitcnt lgkmcnt(0)
	v_cvt_pk_bf16_f32 v42, v10, v11
	ds_read2_b32 v[10:11], v23 offset0:66 offset1:99
	s_waitcnt lgkmcnt(0)
	v_cvt_pk_bf16_f32 v43, v10, v11
	ds_read2_b32 v[10:11], v23 offset0:132 offset1:165
	s_waitcnt lgkmcnt(0)
	v_cvt_pk_bf16_f32 v44, v10, v11
	ds_read2_b32 v[10:11], v23 offset0:198 offset1:231
	s_waitcnt lgkmcnt(0)
	v_cvt_pk_bf16_f32 v45, v10, v11
	v_lshlrev_b64 v[10:11], 11, v[6:7]
	v_lshl_add_u64 v[10:11], v[8:9], 0, v[10:11]
	global_store_dwordx4 v[10:11], v[42:45], off
	ds_read2_b32 v[10:11], v23 offset0:8 offset1:41
	s_waitcnt lgkmcnt(0)
	v_cvt_pk_bf16_f32 v42, v10, v11
	ds_read2_b32 v[10:11], v23 offset0:74 offset1:107
	s_waitcnt lgkmcnt(0)
	v_cvt_pk_bf16_f32 v43, v10, v11
	ds_read2_b32 v[10:11], v23 offset0:140 offset1:173
	s_waitcnt lgkmcnt(0)
	v_cvt_pk_bf16_f32 v44, v10, v11
	ds_read2_b32 v[10:11], v23 offset0:206 offset1:239
	s_waitcnt lgkmcnt(0)
	v_cvt_pk_bf16_f32 v45, v10, v11
	v_add_u32_e32 v10, 8, v6
	v_ashrrev_i32_e32 v11, 31, v10
	v_lshlrev_b64 v[10:11], 11, v[10:11]
	v_lshl_add_u64 v[10:11], v[8:9], 0, v[10:11]
	global_store_dwordx4 v[10:11], v[42:45], off
	ds_read2_b32 v[10:11], v23 offset0:16 offset1:49
	s_waitcnt lgkmcnt(0)
	v_cvt_pk_bf16_f32 v42, v10, v11
	ds_read2_b32 v[10:11], v23 offset0:82 offset1:115
	s_waitcnt lgkmcnt(0)
	v_cvt_pk_bf16_f32 v43, v10, v11
	ds_read2_b32 v[10:11], v23 offset0:148 offset1:181
	s_waitcnt lgkmcnt(0)
	v_cvt_pk_bf16_f32 v44, v10, v11
	ds_read2_b32 v[10:11], v23 offset0:214 offset1:247
	s_waitcnt lgkmcnt(0)
	v_cvt_pk_bf16_f32 v45, v10, v11
	v_add_u32_e32 v10, 16, v6
	v_ashrrev_i32_e32 v11, 31, v10
	v_lshlrev_b64 v[10:11], 11, v[10:11]
	v_lshl_add_u64 v[10:11], v[8:9], 0, v[10:11]
	v_add_u32_e32 v6, 24, v6
	global_store_dwordx4 v[10:11], v[42:45], off
	ds_read2_b32 v[10:11], v23 offset0:24 offset1:57
	v_ashrrev_i32_e32 v7, 31, v6
	s_waitcnt lgkmcnt(0)
	v_cvt_pk_bf16_f32 v42, v10, v11
	ds_read2_b32 v[10:11], v23 offset0:90 offset1:123
	v_lshlrev_b64 v[6:7], 11, v[6:7]
	s_waitcnt lgkmcnt(0)
	v_cvt_pk_bf16_f32 v43, v10, v11
	ds_read2_b32 v[10:11], v23 offset0:156 offset1:189
	v_lshl_add_u64 v[6:7], v[8:9], 0, v[6:7]
	s_waitcnt lgkmcnt(0)
	v_cvt_pk_bf16_f32 v44, v10, v11
	ds_read2_b32 v[10:11], v23 offset0:222 offset1:255
	s_waitcnt lgkmcnt(0)
	v_cvt_pk_bf16_f32 v45, v10, v11
	global_store_dwordx4 v[6:7], v[42:45], off
	s_waitcnt lgkmcnt(0)
	s_andn2_b64 exec, exec, s[6:7]
	s_cbranch_execnz .LBB0_1962

.LBB0_1965:
	v_ashrrev_i32_e32 v6, 31, v40
	v_lshrrev_b32_e32 v6, 27, v6
	v_add_u32_e32 v6, v40, v6
	v_ashrrev_i32_e32 v6, 5, v6
	v_lshlrev_b32_e32 v8, 6, v6
	v_lshlrev_b32_e32 v6, 10, v6
	v_sub_u32_e32 v6, v24, v6
	v_or_b32_e32 v42, v8, v12
	v_ashrrev_i32_e32 v7, 31, v6
	v_ashrrev_i32_e32 v43, 31, v42
	v_lshl_add_u64 v[10:11], v[6:7], 2, v[2:3]
	v_lshlrev_b64 v[42:43], 12, v[42:43]
	v_or_b32_e32 v46, v8, v13
	v_lshl_add_u64 v[42:43], v[10:11], 0, v[42:43]
	v_ashrrev_i32_e32 v47, 31, v46
	global_load_dwordx4 v[42:45], v[42:43], off
	v_lshlrev_b64 v[46:47], 12, v[46:47]
	v_lshl_add_u64 v[46:47], v[10:11], 0, v[46:47]
	global_load_dwordx4 v[46:49], v[46:47], off
	v_add_u32_e32 v6, v6, v12
	v_ashrrev_i32_e32 v9, 31, v8
	v_ashrrev_i32_e32 v7, 31, v6
	v_add_u32_e32 v40, s4, v40
	v_cmp_lt_i32_e32 vcc, s6, v40
	v_add_u32_e32 v24, s5, v24
	s_or_b64 s[2:3], vcc, s[2:3]
	v_or_b32_e32 v192, v8, v14
	v_ashrrev_i32_e32 v193, 31, v192
	v_lshlrev_b64 v[192:193], 12, v[192:193]
	v_or_b32_e32 v196, v8, v15
	v_lshl_add_u64 v[192:193], v[10:11], 0, v[192:193]
	v_ashrrev_i32_e32 v197, 31, v196
	global_load_dwordx4 v[192:195], v[192:193], off
	v_lshlrev_b64 v[196:197], 12, v[196:197]
	v_lshl_add_u64 v[196:197], v[10:11], 0, v[196:197]
	global_load_dwordx4 v[196:199], v[196:197], off
	v_or_b32_e32 v200, v8, v16
	v_ashrrev_i32_e32 v201, 31, v200
	v_lshlrev_b64 v[200:201], 12, v[200:201]
	v_or_b32_e32 v204, v8, v17
	v_lshl_add_u64 v[200:201], v[10:11], 0, v[200:201]
	v_ashrrev_i32_e32 v205, 31, v204
	global_load_dwordx4 v[200:203], v[200:201], off
	v_lshlrev_b64 v[204:205], 12, v[204:205]
	v_lshl_add_u64 v[204:205], v[10:11], 0, v[204:205]
	global_load_dwordx4 v[204:207], v[204:205], off
	v_or_b32_e32 v208, v8, v18
	v_ashrrev_i32_e32 v209, 31, v208
	v_lshlrev_b64 v[208:209], 12, v[208:209]
	v_or_b32_e32 v212, v8, v19
	v_lshl_add_u64 v[208:209], v[10:11], 0, v[208:209]
	v_ashrrev_i32_e32 v213, 31, v212
	global_load_dwordx4 v[208:211], v[208:209], off
	v_lshlrev_b64 v[212:213], 12, v[212:213]
	v_lshl_add_u64 v[10:11], v[10:11], 0, v[212:213]
	global_load_dwordx4 v[212:215], v[10:11], off
	v_lshl_add_u64 v[8:9], v[8:9], 1, v[4:5]
	s_waitcnt vmcnt(7)
	ds_write2_b32 v25, v42, v43 offset1:1
	ds_write2_b32 v25, v44, v45 offset0:2 offset1:3
	s_waitcnt vmcnt(6)
	ds_write2_b32 v26, v46, v47 offset1:1
	ds_write2_b32 v27, v48, v49 offset1:1
	s_waitcnt vmcnt(5)
	ds_write2_b32 v28, v192, v193 offset1:1
	ds_write2_b32 v29, v194, v195 offset1:1
	s_waitcnt vmcnt(4)
	ds_write2_b32 v30, v196, v197 offset1:1
	ds_write2_b32 v31, v198, v199 offset1:1
	s_waitcnt lgkmcnt(7)
	s_waitcnt vmcnt(3)
	ds_write2_b32 v32, v200, v201 offset1:1
	ds_write2_b32 v33, v202, v203 offset1:1
	s_waitcnt vmcnt(2)
	ds_write2_b32 v34, v204, v205 offset1:1
	ds_write2_b32 v35, v206, v207 offset1:1
	s_waitcnt vmcnt(1)
	ds_write2_b32 v36, v208, v209 offset1:1
	ds_write2_b32 v37, v210, v211 offset1:1
	s_waitcnt vmcnt(0)
	ds_write2_b32 v38, v212, v213 offset1:1
	ds_write2_b32 v39, v214, v215 offset1:1
	s_waitcnt lgkmcnt(0)
	ds_read2_b32 v[10:11], v23 offset1:33
	s_waitcnt lgkmcnt(0)
	v_cvt_pk_bf16_f32 v42, v10, v11
	ds_read2_b32 v[10:11], v23 offset0:66 offset1:99
	s_waitcnt lgkmcnt(0)
	v_cvt_pk_bf16_f32 v43, v10, v11
	ds_read2_b32 v[10:11], v23 offset0:132 offset1:165
	s_waitcnt lgkmcnt(0)
	v_cvt_pk_bf16_f32 v44, v10, v11
	ds_read2_b32 v[10:11], v23 offset0:198 offset1:231
	s_waitcnt lgkmcnt(0)
	v_cvt_pk_bf16_f32 v45, v10, v11
	v_lshlrev_b64 v[10:11], 13, v[6:7]
	v_lshl_add_u64 v[10:11], v[8:9], 0, v[10:11]
	global_store_dwordx4 v[10:11], v[42:45], off
	ds_read2_b32 v[10:11], v23 offset0:8 offset1:41
	s_waitcnt lgkmcnt(0)
	v_cvt_pk_bf16_f32 v42, v10, v11
	ds_read2_b32 v[10:11], v23 offset0:74 offset1:107
	s_waitcnt lgkmcnt(0)
	v_cvt_pk_bf16_f32 v43, v10, v11
	ds_read2_b32 v[10:11], v23 offset0:140 offset1:173
	s_waitcnt lgkmcnt(0)
	v_cvt_pk_bf16_f32 v44, v10, v11
	ds_read2_b32 v[10:11], v23 offset0:206 offset1:239
	s_waitcnt lgkmcnt(0)
	v_cvt_pk_bf16_f32 v45, v10, v11
	v_add_u32_e32 v10, 8, v6
	v_ashrrev_i32_e32 v11, 31, v10
	v_lshlrev_b64 v[10:11], 13, v[10:11]
	v_lshl_add_u64 v[10:11], v[8:9], 0, v[10:11]
	global_store_dwordx4 v[10:11], v[42:45], off
	ds_read2_b32 v[10:11], v23 offset0:16 offset1:49
	s_waitcnt lgkmcnt(0)
	v_cvt_pk_bf16_f32 v42, v10, v11
	ds_read2_b32 v[10:11], v23 offset0:82 offset1:115
	s_waitcnt lgkmcnt(0)
	v_cvt_pk_bf16_f32 v43, v10, v11
	ds_read2_b32 v[10:11], v23 offset0:148 offset1:181
	s_waitcnt lgkmcnt(0)
	v_cvt_pk_bf16_f32 v44, v10, v11
	ds_read2_b32 v[10:11], v23 offset0:214 offset1:247
	s_waitcnt lgkmcnt(0)
	v_cvt_pk_bf16_f32 v45, v10, v11
	v_add_u32_e32 v10, 16, v6
	v_ashrrev_i32_e32 v11, 31, v10
	v_lshlrev_b64 v[10:11], 13, v[10:11]
	v_lshl_add_u64 v[10:11], v[8:9], 0, v[10:11]
	v_add_u32_e32 v6, 24, v6
	global_store_dwordx4 v[10:11], v[42:45], off
	ds_read2_b32 v[10:11], v23 offset0:24 offset1:57
	v_ashrrev_i32_e32 v7, 31, v6
	s_waitcnt lgkmcnt(0)
	v_cvt_pk_bf16_f32 v42, v10, v11
	ds_read2_b32 v[10:11], v23 offset0:90 offset1:123
	v_lshlrev_b64 v[6:7], 13, v[6:7]
	s_waitcnt lgkmcnt(0)
	v_cvt_pk_bf16_f32 v43, v10, v11
	ds_read2_b32 v[10:11], v23 offset0:156 offset1:189
	v_lshl_add_u64 v[6:7], v[8:9], 0, v[6:7]
	s_waitcnt lgkmcnt(0)
	v_cvt_pk_bf16_f32 v44, v10, v11
	ds_read2_b32 v[10:11], v23 offset0:222 offset1:255
	s_waitcnt lgkmcnt(0)
	v_cvt_pk_bf16_f32 v45, v10, v11
	global_store_dwordx4 v[6:7], v[42:45], off
	s_waitcnt lgkmcnt(0)
	s_andn2_b64 exec, exec, s[2:3]
	s_cbranch_execnz .LBB0_1965

.LBB0_2012:
	v_ashrrev_i32_e32 v6, 31, v20
	v_lshrrev_b32_e32 v6, 27, v6
	v_add_u32_e32 v6, v20, v6
	v_ashrrev_i32_e32 v6, 5, v6
	v_lshlrev_b32_e32 v8, 6, v6
	v_lshlrev_b32_e32 v6, 10, v6
	v_sub_u32_e32 v6, v21, v6
	v_or_b32_e32 v38, v8, v12
	v_ashrrev_i32_e32 v7, 31, v6
	v_ashrrev_i32_e32 v39, 31, v38
	v_lshl_add_u64 v[10:11], v[6:7], 2, v[2:3]
	v_lshlrev_b64 v[38:39], 12, v[38:39]
	v_or_b32_e32 v42, v8, v13
	v_lshl_add_u64 v[38:39], v[10:11], 0, v[38:39]
	v_ashrrev_i32_e32 v43, 31, v42
	global_load_dwordx4 v[38:41], v[38:39], off
	v_lshlrev_b64 v[42:43], 12, v[42:43]
	v_lshl_add_u64 v[42:43], v[10:11], 0, v[42:43]
	global_load_dwordx4 v[42:45], v[42:43], off
	v_add_u32_e32 v6, v6, v12
	v_ashrrev_i32_e32 v9, 31, v8
	v_ashrrev_i32_e32 v7, 31, v6
	v_add_u32_e32 v20, s4, v20
	v_cmp_lt_i32_e32 vcc, s6, v20
	v_add_u32_e32 v21, s5, v21
	s_or_b64 s[2:3], vcc, s[2:3]
	v_or_b32_e32 v192, v8, v14
	v_ashrrev_i32_e32 v193, 31, v192
	v_lshlrev_b64 v[192:193], 12, v[192:193]
	v_or_b32_e32 v196, v8, v15
	v_lshl_add_u64 v[192:193], v[10:11], 0, v[192:193]
	v_ashrrev_i32_e32 v197, 31, v196
	global_load_dwordx4 v[192:195], v[192:193], off
	v_lshlrev_b64 v[196:197], 12, v[196:197]
	v_lshl_add_u64 v[196:197], v[10:11], 0, v[196:197]
	global_load_dwordx4 v[196:199], v[196:197], off
	v_or_b32_e32 v200, v8, v16
	v_ashrrev_i32_e32 v201, 31, v200
	v_lshlrev_b64 v[200:201], 12, v[200:201]
	v_or_b32_e32 v204, v8, v17
	v_lshl_add_u64 v[200:201], v[10:11], 0, v[200:201]
	v_ashrrev_i32_e32 v205, 31, v204
	global_load_dwordx4 v[200:203], v[200:201], off
	v_lshlrev_b64 v[204:205], 12, v[204:205]
	v_lshl_add_u64 v[204:205], v[10:11], 0, v[204:205]
	global_load_dwordx4 v[204:207], v[204:205], off
	v_or_b32_e32 v208, v8, v18
	v_ashrrev_i32_e32 v209, 31, v208
	v_lshlrev_b64 v[208:209], 12, v[208:209]
	v_or_b32_e32 v212, v8, v19
	v_lshl_add_u64 v[208:209], v[10:11], 0, v[208:209]
	v_ashrrev_i32_e32 v213, 31, v212
	global_load_dwordx4 v[208:211], v[208:209], off
	v_lshlrev_b64 v[212:213], 12, v[212:213]
	v_lshl_add_u64 v[10:11], v[10:11], 0, v[212:213]
	global_load_dwordx4 v[212:215], v[10:11], off
	v_lshl_add_u64 v[8:9], v[8:9], 1, v[4:5]
	s_waitcnt vmcnt(7)
	ds_write2_b32 v23, v38, v39 offset1:1
	ds_write2_b32 v23, v40, v41 offset0:2 offset1:3
	s_waitcnt vmcnt(6)
	ds_write2_b32 v24, v42, v43 offset1:1
	ds_write2_b32 v25, v44, v45 offset1:1
	s_waitcnt vmcnt(5)
	ds_write2_b32 v26, v192, v193 offset1:1
	ds_write2_b32 v27, v194, v195 offset1:1
	s_waitcnt vmcnt(4)
	ds_write2_b32 v28, v196, v197 offset1:1
	ds_write2_b32 v29, v198, v199 offset1:1
	s_waitcnt lgkmcnt(7)
	s_waitcnt vmcnt(3)
	ds_write2_b32 v30, v200, v201 offset1:1
	ds_write2_b32 v31, v202, v203 offset1:1
	s_waitcnt vmcnt(2)
	ds_write2_b32 v32, v204, v205 offset1:1
	ds_write2_b32 v33, v206, v207 offset1:1
	s_waitcnt vmcnt(1)
	ds_write2_b32 v34, v208, v209 offset1:1
	ds_write2_b32 v35, v210, v211 offset1:1
	s_waitcnt vmcnt(0)
	ds_write2_b32 v36, v212, v213 offset1:1
	ds_write2_b32 v37, v214, v215 offset1:1
	s_waitcnt lgkmcnt(0)
	ds_read2_b32 v[10:11], v22 offset1:33
	s_waitcnt lgkmcnt(0)
	v_cvt_pk_bf16_f32 v38, v10, v11
	ds_read2_b32 v[10:11], v22 offset0:66 offset1:99
	s_waitcnt lgkmcnt(0)
	v_cvt_pk_bf16_f32 v39, v10, v11
	ds_read2_b32 v[10:11], v22 offset0:132 offset1:165
	s_waitcnt lgkmcnt(0)
	v_cvt_pk_bf16_f32 v40, v10, v11
	ds_read2_b32 v[10:11], v22 offset0:198 offset1:231
	s_waitcnt lgkmcnt(0)
	v_cvt_pk_bf16_f32 v41, v10, v11
	v_lshlrev_b64 v[10:11], 11, v[6:7]
	v_lshl_add_u64 v[10:11], v[8:9], 0, v[10:11]
	global_store_dwordx4 v[10:11], v[38:41], off
	ds_read2_b32 v[10:11], v22 offset0:8 offset1:41
	s_waitcnt lgkmcnt(0)
	v_cvt_pk_bf16_f32 v38, v10, v11
	ds_read2_b32 v[10:11], v22 offset0:74 offset1:107
	s_waitcnt lgkmcnt(0)
	v_cvt_pk_bf16_f32 v39, v10, v11
	ds_read2_b32 v[10:11], v22 offset0:140 offset1:173
	s_waitcnt lgkmcnt(0)
	v_cvt_pk_bf16_f32 v40, v10, v11
	ds_read2_b32 v[10:11], v22 offset0:206 offset1:239
	s_waitcnt lgkmcnt(0)
	v_cvt_pk_bf16_f32 v41, v10, v11
	v_add_u32_e32 v10, 8, v6
	v_ashrrev_i32_e32 v11, 31, v10
	v_lshlrev_b64 v[10:11], 11, v[10:11]
	v_lshl_add_u64 v[10:11], v[8:9], 0, v[10:11]
	global_store_dwordx4 v[10:11], v[38:41], off
	ds_read2_b32 v[10:11], v22 offset0:16 offset1:49
	s_waitcnt lgkmcnt(0)
	v_cvt_pk_bf16_f32 v38, v10, v11
	ds_read2_b32 v[10:11], v22 offset0:82 offset1:115
	s_waitcnt lgkmcnt(0)
	v_cvt_pk_bf16_f32 v39, v10, v11
	ds_read2_b32 v[10:11], v22 offset0:148 offset1:181
	s_waitcnt lgkmcnt(0)
	v_cvt_pk_bf16_f32 v40, v10, v11
	ds_read2_b32 v[10:11], v22 offset0:214 offset1:247
	s_waitcnt lgkmcnt(0)
	v_cvt_pk_bf16_f32 v41, v10, v11
	v_add_u32_e32 v10, 16, v6
	v_ashrrev_i32_e32 v11, 31, v10
	v_lshlrev_b64 v[10:11], 11, v[10:11]
	v_lshl_add_u64 v[10:11], v[8:9], 0, v[10:11]
	v_add_u32_e32 v6, 24, v6
	global_store_dwordx4 v[10:11], v[38:41], off
	ds_read2_b32 v[10:11], v22 offset0:24 offset1:57
	v_ashrrev_i32_e32 v7, 31, v6
	s_waitcnt lgkmcnt(0)
	v_cvt_pk_bf16_f32 v38, v10, v11
	ds_read2_b32 v[10:11], v22 offset0:90 offset1:123
	v_lshlrev_b64 v[6:7], 11, v[6:7]
	s_waitcnt lgkmcnt(0)
	v_cvt_pk_bf16_f32 v39, v10, v11
	ds_read2_b32 v[10:11], v22 offset0:156 offset1:189
	v_lshl_add_u64 v[6:7], v[8:9], 0, v[6:7]
	s_waitcnt lgkmcnt(0)
	v_cvt_pk_bf16_f32 v40, v10, v11
	ds_read2_b32 v[10:11], v22 offset0:222 offset1:255
	s_waitcnt lgkmcnt(0)
	v_cvt_pk_bf16_f32 v41, v10, v11
	global_store_dwordx4 v[6:7], v[38:41], off
	s_waitcnt lgkmcnt(0)
	s_andn2_b64 exec, exec, s[2:3]
	s_cbranch_execnz .LBB0_2012
